# P7 out-proj latent tiles: hand-written EpiRes epilogue, 16-column halves exchanged between lanes fr and fr^8 (DPP row_ror:8) so every x load / store covers 8 rows x a full 128-byte line; 5-deep x pref
# speedup vs baseline: 1.0096x; 1.0096x over previous
; DEVI unsigned pk_bf16(float lo, float hi) { unsigned r; asm volatile("v_cvt_pk_bf16_f32 %0, %1, %2" : "=v"(r) : "v"(lo), "v"(hi)); return r; }
;   DEVI void preload(Pre& q, int brow, int colb, int wr, int fr, int fq, bool, int slice) const {
;     if (slice >= 0) return;
;     const int r = brow < TL ? (brow >> 12) : 8;
;     const float* gate = modl + (size_t)(r * 9 + gi) * D;
; #pragma unroll
;     for (int n = 0; n < 2; ++n) {
;       const int col = colb + n * 16 + 4 * fq;
;       q.gv[n] = *(const f32x4*)(gate + col);
;       if (xg) q.G[n] = *(const f32x4*)(gvl + (size_t)r * D + col);
;     }
;   }
;   DEVI void operator()(int row, int colb, int fq, const f32x4& a0, const f32x4& a1, float& sqacc, const int slice, const Pre& q) const {
;     if (slice >= 0) {
; #pragma unroll
;       for (int n = 0; n < 2; ++n) {
;         const int col = colb + n * 16 + 4 * fq;
;         const f32x4& a = n ? a1 : a0;
;         uint2 w; w.x = pk_bf16(a[0], a[1]); w.y = pk_bf16(a[2], a[3]);
;         *(uint2*)(ps + ((size_t)slice * TC + (row - TL)) * D + col) = w;
;       }
;       return;
;     }
;     const float* src = row < TL ? xin_lat + (size_t)row * D : xin_ctx + (size_t)(row - TL) * D;
;     const f32x4 xi0 = *(const f32x4*)(src + colb + 4 * fq), xi1 = *(const f32x4*)(src + colb + 16 + 4 * fq);
; #pragma unroll
;     for (int n = 0; n < 2; ++n) {
;       const int col = colb + n * 16 + 4 * fq;
;       const f32x4& a = n ? a1 : a0; const f32x4& xi = n ? xi1 : xi0;
;       f32x4 o;
; #pragma unroll
;       for (int j = 0; j < 4; ++j) o[j] = xi[j] + coef * q.gv[n][j] * a[j];
;       *(f32x4*)(xout + (size_t)row * D + col) = o;
.Lmy_p7_epi:
	v_mbcnt_lo_u32_b32 v149, -1, 0
	v_mbcnt_hi_u32_b32 v149, -1, v149
	s_mov_b32 s52, 0xff00ff
	s_mov_b32 s53, 0xff00ff
	s_mov_b32 s54, 0xff00ff00
	s_mov_b32 s55, 0xff00ff00
	s_lshr_b32 s44, s33, 6
	s_lshr_b32 s45, s44, 2
	s_and_b32 s44, s44, 3
	s_lshl_b32 s45, s45, 18
	s_lshl_b32 s44, s44, 7
	v_and_b32_e32 v150, 15, v149
	v_lshrrev_b32_e32 v149, 4, v149
	v_lshrrev_b32_e32 v148, 3, v150
	v_lshl_add_u32 v148, v148, 2, v149
	v_lshl_add_u32 v148, v148, 4, s44
	v_and_b32_e32 v150, 7, v150
	v_lshl_add_u32 v150, v150, 12, s45
	v_add_u32_e32 v144, v150, v148
	v_add_u32_e32 v145, 0x10000, v144
	v_add_u32_e32 v146, 0x20000, v144
	v_add_u32_e32 v147, 0x30000, v144
	v_add_u32_e32 v212, 0x8000, v144
	v_add_u32_e32 v214, 0x8000, v145
	v_add_u32_e32 v215, 0x8000, v146
	v_add_u32_e32 v216, 0x8000, v147
	s_lshl_b32 s46, s10, 12
	s_lshl_b32 s47, s24, 2
	s_add_u32 s46, s46, s47
	s_add_u32 s36, s70, s46
	s_addc_u32 s37, s71, 0
	s_add_u32 s38, s36, 0x80000
	s_addc_u32 s39, s37, 0
	s_lshr_b32 s46, s10, 12
	s_mul_i32 s46, s46, 9
	s_add_i32 s46, s46, 5
	s_lshl_b32 s46, s46, 12
	s_add_u32 s46, s46, s47
	s_add_u32 s40, s94, s46
	s_addc_u32 s41, s95, 0
	global_load_dwordx4 v[112:115], v148, s[40:41]
	global_load_dwordx4 v[116:119], v148, s[40:41] offset:512
	global_load_dwordx4 v[152:155], v144, s[36:37]
	global_load_dwordx4 v[156:159], v212, s[36:37]
	global_load_dwordx4 v[160:163], v145, s[36:37]
	global_load_dwordx4 v[164:167], v214, s[36:37]
	global_load_dwordx4 v[168:171], v146, s[36:37]
	global_load_dwordx4 v[172:175], v215, s[36:37]
	global_load_dwordx4 v[176:179], v147, s[36:37]
	global_load_dwordx4 v[180:183], v216, s[36:37]
	global_load_dwordx4 v[184:187], v144, s[36:37] offset:512
	global_load_dwordx4 v[188:191], v212, s[36:37] offset:512
	s_mov_b64 vcc, s[52:53]
	v_cndmask_b32_e32 v200, v140, v136, vcc
	v_cndmask_b32_e32 v201, v141, v137, vcc
	v_cndmask_b32_e32 v202, v142, v138, vcc
	v_cndmask_b32_e32 v203, v143, v139, vcc
	v_cndmask_b32_dpp v140, v200, v140, vcc row_ror:8 row_mask:0xf bank_mask:0xf
	v_cndmask_b32_dpp v141, v201, v141, vcc row_ror:8 row_mask:0xf bank_mask:0xf
	v_cndmask_b32_dpp v142, v202, v142, vcc row_ror:8 row_mask:0xf bank_mask:0xf
	v_cndmask_b32_dpp v143, v203, v143, vcc row_ror:8 row_mask:0xf bank_mask:0xf
	s_mov_b64 vcc, s[54:55]
	v_cndmask_b32_dpp v136, v200, v136, vcc row_ror:8 row_mask:0xf bank_mask:0xf
	v_cndmask_b32_dpp v137, v201, v137, vcc row_ror:8 row_mask:0xf bank_mask:0xf
	v_cndmask_b32_dpp v138, v202, v138, vcc row_ror:8 row_mask:0xf bank_mask:0xf
	v_cndmask_b32_dpp v139, v203, v139, vcc row_ror:8 row_mask:0xf bank_mask:0xf
	s_waitcnt vmcnt(8)
	v_pk_fma_f32 v[152:153], v[140:141], v[112:113], v[152:153]
	v_pk_fma_f32 v[154:155], v[142:143], v[114:115], v[154:155]
	v_pk_fma_f32 v[156:157], v[136:137], v[112:113], v[156:157]
	v_pk_fma_f32 v[158:159], v[138:139], v[114:115], v[158:159]
	global_store_dwordx4 v144, v[152:155], s[36:37]
	global_store_dwordx4 v212, v[156:159], s[36:37]
	global_load_dwordx4 v[192:195], v145, s[36:37] offset:512
	global_load_dwordx4 v[196:199], v214, s[36:37] offset:512
	s_mov_b64 vcc, s[52:53]
	v_cndmask_b32_e32 v200, v132, v128, vcc
	v_cndmask_b32_e32 v201, v133, v129, vcc
	v_cndmask_b32_e32 v202, v134, v130, vcc
	v_cndmask_b32_e32 v203, v135, v131, vcc
	v_cndmask_b32_dpp v132, v200, v132, vcc row_ror:8 row_mask:0xf bank_mask:0xf
	v_cndmask_b32_dpp v133, v201, v133, vcc row_ror:8 row_mask:0xf bank_mask:0xf
	v_cndmask_b32_dpp v134, v202, v134, vcc row_ror:8 row_mask:0xf bank_mask:0xf
	v_cndmask_b32_dpp v135, v203, v135, vcc row_ror:8 row_mask:0xf bank_mask:0xf
	s_mov_b64 vcc, s[54:55]
	v_cndmask_b32_dpp v128, v200, v128, vcc row_ror:8 row_mask:0xf bank_mask:0xf
	v_cndmask_b32_dpp v129, v201, v129, vcc row_ror:8 row_mask:0xf bank_mask:0xf
	v_cndmask_b32_dpp v130, v202, v130, vcc row_ror:8 row_mask:0xf bank_mask:0xf
	v_cndmask_b32_dpp v131, v203, v131, vcc row_ror:8 row_mask:0xf bank_mask:0xf
	s_waitcnt vmcnt(10)
	v_pk_fma_f32 v[160:161], v[132:133], v[112:113], v[160:161]
	v_pk_fma_f32 v[162:163], v[134:135], v[114:115], v[162:163]
	v_pk_fma_f32 v[164:165], v[128:129], v[112:113], v[164:165]
	v_pk_fma_f32 v[166:167], v[130:131], v[114:115], v[166:167]
	global_store_dwordx4 v145, v[160:163], s[36:37]
	global_store_dwordx4 v214, v[164:167], s[36:37]
	global_load_dwordx4 v[152:155], v146, s[36:37] offset:512
	global_load_dwordx4 v[156:159], v215, s[36:37] offset:512
	s_mov_b64 vcc, s[52:53]
	v_cndmask_b32_e32 v200, v124, v120, vcc
	v_cndmask_b32_e32 v201, v125, v121, vcc
	v_cndmask_b32_e32 v202, v126, v122, vcc
	v_cndmask_b32_e32 v203, v127, v123, vcc
	v_cndmask_b32_dpp v124, v200, v124, vcc row_ror:8 row_mask:0xf bank_mask:0xf
	v_cndmask_b32_dpp v125, v201, v125, vcc row_ror:8 row_mask:0xf bank_mask:0xf
	v_cndmask_b32_dpp v126, v202, v126, vcc row_ror:8 row_mask:0xf bank_mask:0xf
	v_cndmask_b32_dpp v127, v203, v127, vcc row_ror:8 row_mask:0xf bank_mask:0xf
	s_mov_b64 vcc, s[54:55]
	v_cndmask_b32_dpp v120, v200, v120, vcc row_ror:8 row_mask:0xf bank_mask:0xf
	v_cndmask_b32_dpp v121, v201, v121, vcc row_ror:8 row_mask:0xf bank_mask:0xf
	v_cndmask_b32_dpp v122, v202, v122, vcc row_ror:8 row_mask:0xf bank_mask:0xf
	v_cndmask_b32_dpp v123, v203, v123, vcc row_ror:8 row_mask:0xf bank_mask:0xf
	s_waitcnt vmcnt(12)
; template <class Epi>
; DEVI void gemm_phase(const Params& p, const u16* __restrict__ A, const u16* __restrict__ Bt, const int M, const int N, const int K, const int Msplit, const Epi& epi) {
;     ...
; #pragma unroll
;       for (int ai = 0; ai < 2; ++ai)
; #pragma unroll
;         for (int bj = 0; bj < 2; ++bj) {
;           const int colb = bcol + bj * HALF + wc2 * 32;
;           typename Epi::Pre pre;
;           if constexpr (Epi::NRM || Epi::SQ) epi.preload(pre, brow, colb, wr2, fr2, fq2, nrm, slcur);
; #pragma unroll
;           for (int m = 0; m < 4; ++m) {
;             const int rloc = ai * HALF + wr2 * 64 + m * 16;
;             if constexpr (Epi::SQ) epi(brow + rloc + fr2, colb, fq2, acc[ai][bj][m][0], acc[ai][bj][m][1], sq[ai * 4 + m], slcur, pre);
;             else if constexpr (Epi::TR) { float rv = 1.f; if (nrm) rv = rl[rloc + fr2]; epi(brow + rloc + fr2, colb, fq2, acc[ai][bj][m][0], acc[ai][bj][m][1], rv, nrm, pre); }
;             else { f32x4 rv = {1.f, 1.f, 1.f, 1.f}; if (nrm) rv = *(const f32x4*)(rl + rloc + fq2 * 4); epi(brow + rloc + fq2 * 4, colb, fr2, acc[ai][bj][m][0], acc[ai][bj][m][1], rv, nrm, pre); }
;           }
;   DEVI void operator()(int row, int colb, int fq, const f32x4& a0, const f32x4& a1, float& sqacc, const int slice, const Pre& q) const {
;     ...
;     const float* src = row < TL ? xin_lat + (size_t)row * D : xin_ctx + (size_t)(row - TL) * D;
;     const f32x4 xi0 = *(const f32x4*)(src + colb + 4 * fq), xi1 = *(const f32x4*)(src + colb + 16 + 4 * fq);
; #pragma unroll
;     for (int n = 0; n < 2; ++n) {
;       const int col = colb + n * 16 + 4 * fq;
;       const f32x4& a = n ? a1 : a0; const f32x4& xi = n ? xi1 : xi0;
;       f32x4 o;
; #pragma unroll
;       for (int j = 0; j < 4; ++j) o[j] = xi[j] + coef * q.gv[n][j] * a[j];
;       *(f32x4*)(xout + (size_t)row * D + col) = o;
	v_pk_fma_f32 v[168:169], v[124:125], v[112:113], v[168:169]
	v_pk_fma_f32 v[170:171], v[126:127], v[114:115], v[170:171]
	v_pk_fma_f32 v[172:173], v[120:121], v[112:113], v[172:173]
	v_pk_fma_f32 v[174:175], v[122:123], v[114:115], v[174:175]
	global_store_dwordx4 v146, v[168:171], s[36:37]
	global_store_dwordx4 v215, v[172:175], s[36:37]
	global_load_dwordx4 v[160:163], v147, s[36:37] offset:512
	global_load_dwordx4 v[164:167], v216, s[36:37] offset:512
	s_mov_b64 vcc, s[52:53]
	v_cndmask_b32_e32 v200, v68, v64, vcc
	v_cndmask_b32_e32 v201, v69, v65, vcc
	v_cndmask_b32_e32 v202, v70, v66, vcc
	v_cndmask_b32_e32 v203, v71, v67, vcc
	v_cndmask_b32_dpp v68, v200, v68, vcc row_ror:8 row_mask:0xf bank_mask:0xf
	v_cndmask_b32_dpp v69, v201, v69, vcc row_ror:8 row_mask:0xf bank_mask:0xf
	v_cndmask_b32_dpp v70, v202, v70, vcc row_ror:8 row_mask:0xf bank_mask:0xf
	v_cndmask_b32_dpp v71, v203, v71, vcc row_ror:8 row_mask:0xf bank_mask:0xf
	s_mov_b64 vcc, s[54:55]
	v_cndmask_b32_dpp v64, v200, v64, vcc row_ror:8 row_mask:0xf bank_mask:0xf
	v_cndmask_b32_dpp v65, v201, v65, vcc row_ror:8 row_mask:0xf bank_mask:0xf
	v_cndmask_b32_dpp v66, v202, v66, vcc row_ror:8 row_mask:0xf bank_mask:0xf
	v_cndmask_b32_dpp v67, v203, v67, vcc row_ror:8 row_mask:0xf bank_mask:0xf
	s_waitcnt vmcnt(14)
	v_pk_fma_f32 v[176:177], v[68:69], v[112:113], v[176:177]
	v_pk_fma_f32 v[178:179], v[70:71], v[114:115], v[178:179]
	v_pk_fma_f32 v[180:181], v[64:65], v[112:113], v[180:181]
	v_pk_fma_f32 v[182:183], v[66:67], v[114:115], v[182:183]
	global_store_dwordx4 v147, v[176:179], s[36:37]
	global_store_dwordx4 v216, v[180:183], s[36:37]
	global_load_dwordx4 v[168:171], v144, s[38:39]
	global_load_dwordx4 v[172:175], v212, s[38:39]
	s_mov_b64 vcc, s[52:53]
	v_cndmask_b32_e32 v200, v108, v104, vcc
	v_cndmask_b32_e32 v201, v109, v105, vcc
	v_cndmask_b32_e32 v202, v110, v106, vcc
	v_cndmask_b32_e32 v203, v111, v107, vcc
	v_cndmask_b32_dpp v108, v200, v108, vcc row_ror:8 row_mask:0xf bank_mask:0xf
	v_cndmask_b32_dpp v109, v201, v109, vcc row_ror:8 row_mask:0xf bank_mask:0xf
	v_cndmask_b32_dpp v110, v202, v110, vcc row_ror:8 row_mask:0xf bank_mask:0xf
	v_cndmask_b32_dpp v111, v203, v111, vcc row_ror:8 row_mask:0xf bank_mask:0xf
	s_mov_b64 vcc, s[54:55]
	v_cndmask_b32_dpp v104, v200, v104, vcc row_ror:8 row_mask:0xf bank_mask:0xf
	v_cndmask_b32_dpp v105, v201, v105, vcc row_ror:8 row_mask:0xf bank_mask:0xf
	v_cndmask_b32_dpp v106, v202, v106, vcc row_ror:8 row_mask:0xf bank_mask:0xf
	v_cndmask_b32_dpp v107, v203, v107, vcc row_ror:8 row_mask:0xf bank_mask:0xf
	s_waitcnt vmcnt(16)
	v_pk_fma_f32 v[184:185], v[108:109], v[116:117], v[184:185]
	v_pk_fma_f32 v[186:187], v[110:111], v[118:119], v[186:187]
	v_pk_fma_f32 v[188:189], v[104:105], v[116:117], v[188:189]
	v_pk_fma_f32 v[190:191], v[106:107], v[118:119], v[190:191]
	global_store_dwordx4 v144, v[184:187], s[36:37] offset:512
	global_store_dwordx4 v212, v[188:191], s[36:37] offset:512
	global_load_dwordx4 v[176:179], v145, s[38:39]
	global_load_dwordx4 v[180:183], v214, s[38:39]
	s_mov_b64 vcc, s[52:53]
	v_cndmask_b32_e32 v200, v100, v96, vcc
	v_cndmask_b32_e32 v201, v101, v97, vcc
	v_cndmask_b32_e32 v202, v102, v98, vcc
	v_cndmask_b32_e32 v203, v103, v99, vcc
	v_cndmask_b32_dpp v100, v200, v100, vcc row_ror:8 row_mask:0xf bank_mask:0xf
	v_cndmask_b32_dpp v101, v201, v101, vcc row_ror:8 row_mask:0xf bank_mask:0xf
	v_cndmask_b32_dpp v102, v202, v102, vcc row_ror:8 row_mask:0xf bank_mask:0xf
	v_cndmask_b32_dpp v103, v203, v103, vcc row_ror:8 row_mask:0xf bank_mask:0xf
	s_mov_b64 vcc, s[54:55]
	v_cndmask_b32_dpp v96, v200, v96, vcc row_ror:8 row_mask:0xf bank_mask:0xf
	v_cndmask_b32_dpp v97, v201, v97, vcc row_ror:8 row_mask:0xf bank_mask:0xf
	v_cndmask_b32_dpp v98, v202, v98, vcc row_ror:8 row_mask:0xf bank_mask:0xf
	v_cndmask_b32_dpp v99, v203, v99, vcc row_ror:8 row_mask:0xf bank_mask:0xf
	s_waitcnt vmcnt(16)
	v_pk_fma_f32 v[192:193], v[100:101], v[116:117], v[192:193]
	v_pk_fma_f32 v[194:195], v[102:103], v[118:119], v[194:195]
	v_pk_fma_f32 v[196:197], v[96:97], v[116:117], v[196:197]
	v_pk_fma_f32 v[198:199], v[98:99], v[118:119], v[198:199]
	global_store_dwordx4 v145, v[192:195], s[36:37] offset:512
	global_store_dwordx4 v214, v[196:199], s[36:37] offset:512
	global_load_dwordx4 v[184:187], v146, s[38:39]
	global_load_dwordx4 v[188:191], v215, s[38:39]
	s_mov_b64 vcc, s[52:53]
	v_cndmask_b32_e32 v200, v92, v88, vcc
	v_cndmask_b32_e32 v201, v93, v89, vcc
	v_cndmask_b32_e32 v202, v94, v90, vcc
	v_cndmask_b32_e32 v203, v95, v91, vcc
	v_cndmask_b32_dpp v92, v200, v92, vcc row_ror:8 row_mask:0xf bank_mask:0xf
	v_cndmask_b32_dpp v93, v201, v93, vcc row_ror:8 row_mask:0xf bank_mask:0xf
	v_cndmask_b32_dpp v94, v202, v94, vcc row_ror:8 row_mask:0xf bank_mask:0xf
	v_cndmask_b32_dpp v95, v203, v95, vcc row_ror:8 row_mask:0xf bank_mask:0xf
	s_mov_b64 vcc, s[54:55]
	v_cndmask_b32_dpp v88, v200, v88, vcc row_ror:8 row_mask:0xf bank_mask:0xf
	v_cndmask_b32_dpp v89, v201, v89, vcc row_ror:8 row_mask:0xf bank_mask:0xf
	v_cndmask_b32_dpp v90, v202, v90, vcc row_ror:8 row_mask:0xf bank_mask:0xf
	v_cndmask_b32_dpp v91, v203, v91, vcc row_ror:8 row_mask:0xf bank_mask:0xf
	s_waitcnt vmcnt(16)
; template <class Epi>
; DEVI void gemm_phase(const Params& p, const u16* __restrict__ A, const u16* __restrict__ Bt, const int M, const int N, const int K, const int Msplit, const Epi& epi) {
;     ...
; #pragma unroll
;       for (int ai = 0; ai < 2; ++ai)
; #pragma unroll
;         for (int bj = 0; bj < 2; ++bj) {
;           const int colb = bcol + bj * HALF + wc2 * 32;
;           typename Epi::Pre pre;
;           if constexpr (Epi::NRM || Epi::SQ) epi.preload(pre, brow, colb, wr2, fr2, fq2, nrm, slcur);
; #pragma unroll
;           for (int m = 0; m < 4; ++m) {
;             const int rloc = ai * HALF + wr2 * 64 + m * 16;
;             if constexpr (Epi::SQ) epi(brow + rloc + fr2, colb, fq2, acc[ai][bj][m][0], acc[ai][bj][m][1], sq[ai * 4 + m], slcur, pre);
;             else if constexpr (Epi::TR) { float rv = 1.f; if (nrm) rv = rl[rloc + fr2]; epi(brow + rloc + fr2, colb, fq2, acc[ai][bj][m][0], acc[ai][bj][m][1], rv, nrm, pre); }
;             else { f32x4 rv = {1.f, 1.f, 1.f, 1.f}; if (nrm) rv = *(const f32x4*)(rl + rloc + fq2 * 4); epi(brow + rloc + fq2 * 4, colb, fr2, acc[ai][bj][m][0], acc[ai][bj][m][1], rv, nrm, pre); }
;           }
;   DEVI void operator()(int row, int colb, int fq, const f32x4& a0, const f32x4& a1, float& sqacc, const int slice, const Pre& q) const {
;     ...
;     const float* src = row < TL ? xin_lat + (size_t)row * D : xin_ctx + (size_t)(row - TL) * D;
;     const f32x4 xi0 = *(const f32x4*)(src + colb + 4 * fq), xi1 = *(const f32x4*)(src + colb + 16 + 4 * fq);
; #pragma unroll
;     for (int n = 0; n < 2; ++n) {
;       const int col = colb + n * 16 + 4 * fq;
;       const f32x4& a = n ? a1 : a0; const f32x4& xi = n ? xi1 : xi0;
;       f32x4 o;
; #pragma unroll
;       for (int j = 0; j < 4; ++j) o[j] = xi[j] + coef * q.gv[n][j] * a[j];
;       *(f32x4*)(xout + (size_t)row * D + col) = o;
	v_pk_fma_f32 v[152:153], v[92:93], v[116:117], v[152:153]
	v_pk_fma_f32 v[154:155], v[94:95], v[118:119], v[154:155]
	v_pk_fma_f32 v[156:157], v[88:89], v[116:117], v[156:157]
	v_pk_fma_f32 v[158:159], v[90:91], v[118:119], v[158:159]
	global_store_dwordx4 v146, v[152:155], s[36:37] offset:512
	global_store_dwordx4 v215, v[156:159], s[36:37] offset:512
	global_load_dwordx4 v[192:195], v147, s[38:39]
	global_load_dwordx4 v[196:199], v216, s[38:39]
	s_mov_b64 vcc, s[52:53]
	v_cndmask_b32_e32 v200, v84, v80, vcc
	v_cndmask_b32_e32 v201, v85, v81, vcc
	v_cndmask_b32_e32 v202, v86, v82, vcc
	v_cndmask_b32_e32 v203, v87, v83, vcc
	v_cndmask_b32_dpp v84, v200, v84, vcc row_ror:8 row_mask:0xf bank_mask:0xf
	v_cndmask_b32_dpp v85, v201, v85, vcc row_ror:8 row_mask:0xf bank_mask:0xf
	v_cndmask_b32_dpp v86, v202, v86, vcc row_ror:8 row_mask:0xf bank_mask:0xf
	v_cndmask_b32_dpp v87, v203, v87, vcc row_ror:8 row_mask:0xf bank_mask:0xf
	s_mov_b64 vcc, s[54:55]
	v_cndmask_b32_dpp v80, v200, v80, vcc row_ror:8 row_mask:0xf bank_mask:0xf
	v_cndmask_b32_dpp v81, v201, v81, vcc row_ror:8 row_mask:0xf bank_mask:0xf
	v_cndmask_b32_dpp v82, v202, v82, vcc row_ror:8 row_mask:0xf bank_mask:0xf
	v_cndmask_b32_dpp v83, v203, v83, vcc row_ror:8 row_mask:0xf bank_mask:0xf
	s_waitcnt vmcnt(16)
	v_pk_fma_f32 v[160:161], v[84:85], v[116:117], v[160:161]
	v_pk_fma_f32 v[162:163], v[86:87], v[118:119], v[162:163]
	v_pk_fma_f32 v[164:165], v[80:81], v[116:117], v[164:165]
	v_pk_fma_f32 v[166:167], v[82:83], v[118:119], v[166:167]
	global_store_dwordx4 v147, v[160:163], s[36:37] offset:512
	global_store_dwordx4 v216, v[164:167], s[36:37] offset:512
	global_load_dwordx4 v[152:155], v144, s[38:39] offset:512
	global_load_dwordx4 v[156:159], v212, s[38:39] offset:512
	s_mov_b64 vcc, s[52:53]
	v_cndmask_b32_e32 v200, v76, v72, vcc
	v_cndmask_b32_e32 v201, v77, v73, vcc
	v_cndmask_b32_e32 v202, v78, v74, vcc
	v_cndmask_b32_e32 v203, v79, v75, vcc
	v_cndmask_b32_dpp v76, v200, v76, vcc row_ror:8 row_mask:0xf bank_mask:0xf
	v_cndmask_b32_dpp v77, v201, v77, vcc row_ror:8 row_mask:0xf bank_mask:0xf
	v_cndmask_b32_dpp v78, v202, v78, vcc row_ror:8 row_mask:0xf bank_mask:0xf
	v_cndmask_b32_dpp v79, v203, v79, vcc row_ror:8 row_mask:0xf bank_mask:0xf
	s_mov_b64 vcc, s[54:55]
	v_cndmask_b32_dpp v72, v200, v72, vcc row_ror:8 row_mask:0xf bank_mask:0xf
	v_cndmask_b32_dpp v73, v201, v73, vcc row_ror:8 row_mask:0xf bank_mask:0xf
	v_cndmask_b32_dpp v74, v202, v74, vcc row_ror:8 row_mask:0xf bank_mask:0xf
	v_cndmask_b32_dpp v75, v203, v75, vcc row_ror:8 row_mask:0xf bank_mask:0xf
	s_waitcnt vmcnt(16)
	v_pk_fma_f32 v[168:169], v[76:77], v[112:113], v[168:169]
	v_pk_fma_f32 v[170:171], v[78:79], v[114:115], v[170:171]
	v_pk_fma_f32 v[172:173], v[72:73], v[112:113], v[172:173]
	v_pk_fma_f32 v[174:175], v[74:75], v[114:115], v[174:175]
	global_store_dwordx4 v144, v[168:171], s[38:39]
	global_store_dwordx4 v212, v[172:175], s[38:39]
	global_load_dwordx4 v[160:163], v145, s[38:39] offset:512
	global_load_dwordx4 v[164:167], v214, s[38:39] offset:512
	s_mov_b64 vcc, s[52:53]
	v_cndmask_b32_e32 v200, v60, v56, vcc
	v_cndmask_b32_e32 v201, v61, v57, vcc
	v_cndmask_b32_e32 v202, v62, v58, vcc
	v_cndmask_b32_e32 v203, v63, v59, vcc
	v_cndmask_b32_dpp v60, v200, v60, vcc row_ror:8 row_mask:0xf bank_mask:0xf
	v_cndmask_b32_dpp v61, v201, v61, vcc row_ror:8 row_mask:0xf bank_mask:0xf
	v_cndmask_b32_dpp v62, v202, v62, vcc row_ror:8 row_mask:0xf bank_mask:0xf
	v_cndmask_b32_dpp v63, v203, v63, vcc row_ror:8 row_mask:0xf bank_mask:0xf
	s_mov_b64 vcc, s[54:55]
	v_cndmask_b32_dpp v56, v200, v56, vcc row_ror:8 row_mask:0xf bank_mask:0xf
	v_cndmask_b32_dpp v57, v201, v57, vcc row_ror:8 row_mask:0xf bank_mask:0xf
	v_cndmask_b32_dpp v58, v202, v58, vcc row_ror:8 row_mask:0xf bank_mask:0xf
	v_cndmask_b32_dpp v59, v203, v59, vcc row_ror:8 row_mask:0xf bank_mask:0xf
	s_waitcnt vmcnt(16)
	v_pk_fma_f32 v[176:177], v[60:61], v[112:113], v[176:177]
	v_pk_fma_f32 v[178:179], v[62:63], v[114:115], v[178:179]
	v_pk_fma_f32 v[180:181], v[56:57], v[112:113], v[180:181]
	v_pk_fma_f32 v[182:183], v[58:59], v[114:115], v[182:183]
	global_store_dwordx4 v145, v[176:179], s[38:39]
	global_store_dwordx4 v214, v[180:183], s[38:39]
	global_load_dwordx4 v[168:171], v146, s[38:39] offset:512
	global_load_dwordx4 v[172:175], v215, s[38:39] offset:512
	s_mov_b64 vcc, s[52:53]
	v_cndmask_b32_e32 v200, v52, v48, vcc
	v_cndmask_b32_e32 v201, v53, v49, vcc
	v_cndmask_b32_e32 v202, v54, v50, vcc
	v_cndmask_b32_e32 v203, v55, v51, vcc
	v_cndmask_b32_dpp v52, v200, v52, vcc row_ror:8 row_mask:0xf bank_mask:0xf
	v_cndmask_b32_dpp v53, v201, v53, vcc row_ror:8 row_mask:0xf bank_mask:0xf
	v_cndmask_b32_dpp v54, v202, v54, vcc row_ror:8 row_mask:0xf bank_mask:0xf
	v_cndmask_b32_dpp v55, v203, v55, vcc row_ror:8 row_mask:0xf bank_mask:0xf
	s_mov_b64 vcc, s[54:55]
	v_cndmask_b32_dpp v48, v200, v48, vcc row_ror:8 row_mask:0xf bank_mask:0xf
	v_cndmask_b32_dpp v49, v201, v49, vcc row_ror:8 row_mask:0xf bank_mask:0xf
	v_cndmask_b32_dpp v50, v202, v50, vcc row_ror:8 row_mask:0xf bank_mask:0xf
	v_cndmask_b32_dpp v51, v203, v51, vcc row_ror:8 row_mask:0xf bank_mask:0xf
	s_waitcnt vmcnt(16)
; template <class Epi>
; DEVI void gemm_phase(const Params& p, const u16* __restrict__ A, const u16* __restrict__ Bt, const int M, const int N, const int K, const int Msplit, const Epi& epi) {
;     ...
; #pragma unroll
;       for (int ai = 0; ai < 2; ++ai)
; #pragma unroll
;         for (int bj = 0; bj < 2; ++bj) {
;           const int colb = bcol + bj * HALF + wc2 * 32;
;           typename Epi::Pre pre;
;           if constexpr (Epi::NRM || Epi::SQ) epi.preload(pre, brow, colb, wr2, fr2, fq2, nrm, slcur);
; #pragma unroll
;           for (int m = 0; m < 4; ++m) {
;             const int rloc = ai * HALF + wr2 * 64 + m * 16;
;             if constexpr (Epi::SQ) epi(brow + rloc + fr2, colb, fq2, acc[ai][bj][m][0], acc[ai][bj][m][1], sq[ai * 4 + m], slcur, pre);
;             else if constexpr (Epi::TR) { float rv = 1.f; if (nrm) rv = rl[rloc + fr2]; epi(brow + rloc + fr2, colb, fq2, acc[ai][bj][m][0], acc[ai][bj][m][1], rv, nrm, pre); }
;             else { f32x4 rv = {1.f, 1.f, 1.f, 1.f}; if (nrm) rv = *(const f32x4*)(rl + rloc + fq2 * 4); epi(brow + rloc + fq2 * 4, colb, fr2, acc[ai][bj][m][0], acc[ai][bj][m][1], rv, nrm, pre); }
;           }
;   DEVI void operator()(int row, int colb, int fq, const f32x4& a0, const f32x4& a1, float& sqacc, const int slice, const Pre& q) const {
;     ...
;     const float* src = row < TL ? xin_lat + (size_t)row * D : xin_ctx + (size_t)(row - TL) * D;
;     const f32x4 xi0 = *(const f32x4*)(src + colb + 4 * fq), xi1 = *(const f32x4*)(src + colb + 16 + 4 * fq);
; #pragma unroll
;     for (int n = 0; n < 2; ++n) {
;       const int col = colb + n * 16 + 4 * fq;
;       const f32x4& a = n ? a1 : a0; const f32x4& xi = n ? xi1 : xi0;
;       f32x4 o;
; #pragma unroll
;       for (int j = 0; j < 4; ++j) o[j] = xi[j] + coef * q.gv[n][j] * a[j];
;       *(f32x4*)(xout + (size_t)row * D + col) = o;
	v_pk_fma_f32 v[184:185], v[52:53], v[112:113], v[184:185]
	v_pk_fma_f32 v[186:187], v[54:55], v[114:115], v[186:187]
	v_pk_fma_f32 v[188:189], v[48:49], v[112:113], v[188:189]
	v_pk_fma_f32 v[190:191], v[50:51], v[114:115], v[190:191]
	global_store_dwordx4 v146, v[184:187], s[38:39]
	global_store_dwordx4 v215, v[188:191], s[38:39]
	global_load_dwordx4 v[176:179], v147, s[38:39] offset:512
	global_load_dwordx4 v[180:183], v216, s[38:39] offset:512
	s_mov_b64 vcc, s[52:53]
	v_cndmask_b32_e32 v200, v44, v40, vcc
	v_cndmask_b32_e32 v201, v45, v41, vcc
	v_cndmask_b32_e32 v202, v46, v42, vcc
	v_cndmask_b32_e32 v203, v47, v43, vcc
	v_cndmask_b32_dpp v44, v200, v44, vcc row_ror:8 row_mask:0xf bank_mask:0xf
	v_cndmask_b32_dpp v45, v201, v45, vcc row_ror:8 row_mask:0xf bank_mask:0xf
	v_cndmask_b32_dpp v46, v202, v46, vcc row_ror:8 row_mask:0xf bank_mask:0xf
	v_cndmask_b32_dpp v47, v203, v47, vcc row_ror:8 row_mask:0xf bank_mask:0xf
	s_mov_b64 vcc, s[54:55]
	v_cndmask_b32_dpp v40, v200, v40, vcc row_ror:8 row_mask:0xf bank_mask:0xf
	v_cndmask_b32_dpp v41, v201, v41, vcc row_ror:8 row_mask:0xf bank_mask:0xf
	v_cndmask_b32_dpp v42, v202, v42, vcc row_ror:8 row_mask:0xf bank_mask:0xf
	v_cndmask_b32_dpp v43, v203, v43, vcc row_ror:8 row_mask:0xf bank_mask:0xf
	s_waitcnt vmcnt(16)
	v_pk_fma_f32 v[192:193], v[44:45], v[112:113], v[192:193]
	v_pk_fma_f32 v[194:195], v[46:47], v[114:115], v[194:195]
	v_pk_fma_f32 v[196:197], v[40:41], v[112:113], v[196:197]
	v_pk_fma_f32 v[198:199], v[42:43], v[114:115], v[198:199]
	global_store_dwordx4 v147, v[192:195], s[38:39]
	global_store_dwordx4 v216, v[196:199], s[38:39]
	s_mov_b64 vcc, s[52:53]
	v_cndmask_b32_e32 v200, v36, v32, vcc
	v_cndmask_b32_e32 v201, v37, v33, vcc
	v_cndmask_b32_e32 v202, v38, v34, vcc
	v_cndmask_b32_e32 v203, v39, v35, vcc
	v_cndmask_b32_dpp v36, v200, v36, vcc row_ror:8 row_mask:0xf bank_mask:0xf
	v_cndmask_b32_dpp v37, v201, v37, vcc row_ror:8 row_mask:0xf bank_mask:0xf
	v_cndmask_b32_dpp v38, v202, v38, vcc row_ror:8 row_mask:0xf bank_mask:0xf
	v_cndmask_b32_dpp v39, v203, v39, vcc row_ror:8 row_mask:0xf bank_mask:0xf
	s_mov_b64 vcc, s[54:55]
	v_cndmask_b32_dpp v32, v200, v32, vcc row_ror:8 row_mask:0xf bank_mask:0xf
	v_cndmask_b32_dpp v33, v201, v33, vcc row_ror:8 row_mask:0xf bank_mask:0xf
	v_cndmask_b32_dpp v34, v202, v34, vcc row_ror:8 row_mask:0xf bank_mask:0xf
	v_cndmask_b32_dpp v35, v203, v35, vcc row_ror:8 row_mask:0xf bank_mask:0xf
	s_waitcnt vmcnt(14)
	v_pk_fma_f32 v[152:153], v[36:37], v[116:117], v[152:153]
	v_pk_fma_f32 v[154:155], v[38:39], v[118:119], v[154:155]
	v_pk_fma_f32 v[156:157], v[32:33], v[116:117], v[156:157]
	v_pk_fma_f32 v[158:159], v[34:35], v[118:119], v[158:159]
	global_store_dwordx4 v144, v[152:155], s[38:39] offset:512
	global_store_dwordx4 v212, v[156:159], s[38:39] offset:512
	s_mov_b64 vcc, s[52:53]
	v_cndmask_b32_e32 v200, v28, v24, vcc
	v_cndmask_b32_e32 v201, v29, v25, vcc
	v_cndmask_b32_e32 v202, v30, v26, vcc
	v_cndmask_b32_e32 v203, v31, v27, vcc
	v_cndmask_b32_dpp v28, v200, v28, vcc row_ror:8 row_mask:0xf bank_mask:0xf
	v_cndmask_b32_dpp v29, v201, v29, vcc row_ror:8 row_mask:0xf bank_mask:0xf
	v_cndmask_b32_dpp v30, v202, v30, vcc row_ror:8 row_mask:0xf bank_mask:0xf
	v_cndmask_b32_dpp v31, v203, v31, vcc row_ror:8 row_mask:0xf bank_mask:0xf
	s_mov_b64 vcc, s[54:55]
	v_cndmask_b32_dpp v24, v200, v24, vcc row_ror:8 row_mask:0xf bank_mask:0xf
	v_cndmask_b32_dpp v25, v201, v25, vcc row_ror:8 row_mask:0xf bank_mask:0xf
	v_cndmask_b32_dpp v26, v202, v26, vcc row_ror:8 row_mask:0xf bank_mask:0xf
	v_cndmask_b32_dpp v27, v203, v27, vcc row_ror:8 row_mask:0xf bank_mask:0xf
	s_waitcnt vmcnt(12)
	v_pk_fma_f32 v[160:161], v[28:29], v[116:117], v[160:161]
	v_pk_fma_f32 v[162:163], v[30:31], v[118:119], v[162:163]
	v_pk_fma_f32 v[164:165], v[24:25], v[116:117], v[164:165]
	v_pk_fma_f32 v[166:167], v[26:27], v[118:119], v[166:167]
	global_store_dwordx4 v145, v[160:163], s[38:39] offset:512
	global_store_dwordx4 v214, v[164:167], s[38:39] offset:512
	s_mov_b64 vcc, s[52:53]
	v_cndmask_b32_e32 v200, v20, v16, vcc
	v_cndmask_b32_e32 v201, v21, v17, vcc
	v_cndmask_b32_e32 v202, v22, v18, vcc
	v_cndmask_b32_e32 v203, v23, v19, vcc
	v_cndmask_b32_dpp v20, v200, v20, vcc row_ror:8 row_mask:0xf bank_mask:0xf
	v_cndmask_b32_dpp v21, v201, v21, vcc row_ror:8 row_mask:0xf bank_mask:0xf
	v_cndmask_b32_dpp v22, v202, v22, vcc row_ror:8 row_mask:0xf bank_mask:0xf
	v_cndmask_b32_dpp v23, v203, v23, vcc row_ror:8 row_mask:0xf bank_mask:0xf
	s_mov_b64 vcc, s[54:55]
	v_cndmask_b32_dpp v16, v200, v16, vcc row_ror:8 row_mask:0xf bank_mask:0xf
	v_cndmask_b32_dpp v17, v201, v17, vcc row_ror:8 row_mask:0xf bank_mask:0xf
	v_cndmask_b32_dpp v18, v202, v18, vcc row_ror:8 row_mask:0xf bank_mask:0xf
	v_cndmask_b32_dpp v19, v203, v19, vcc row_ror:8 row_mask:0xf bank_mask:0xf
	s_waitcnt vmcnt(10)
	v_pk_fma_f32 v[168:169], v[20:21], v[116:117], v[168:169]
	v_pk_fma_f32 v[170:171], v[22:23], v[118:119], v[170:171]
	v_pk_fma_f32 v[172:173], v[16:17], v[116:117], v[172:173]
	v_pk_fma_f32 v[174:175], v[18:19], v[118:119], v[174:175]
	global_store_dwordx4 v146, v[168:171], s[38:39] offset:512
	global_store_dwordx4 v215, v[172:175], s[38:39] offset:512
	s_mov_b64 vcc, s[52:53]
	v_cndmask_b32_e32 v200, v12, v8, vcc
	v_cndmask_b32_e32 v201, v13, v9, vcc
	v_cndmask_b32_e32 v202, v14, v10, vcc
	v_cndmask_b32_e32 v203, v15, v11, vcc
	v_cndmask_b32_dpp v12, v200, v12, vcc row_ror:8 row_mask:0xf bank_mask:0xf
	v_cndmask_b32_dpp v13, v201, v13, vcc row_ror:8 row_mask:0xf bank_mask:0xf
	v_cndmask_b32_dpp v14, v202, v14, vcc row_ror:8 row_mask:0xf bank_mask:0xf
	v_cndmask_b32_dpp v15, v203, v15, vcc row_ror:8 row_mask:0xf bank_mask:0xf
	s_mov_b64 vcc, s[54:55]
	v_cndmask_b32_dpp v8, v200, v8, vcc row_ror:8 row_mask:0xf bank_mask:0xf
	v_cndmask_b32_dpp v9, v201, v9, vcc row_ror:8 row_mask:0xf bank_mask:0xf
	v_cndmask_b32_dpp v10, v202, v10, vcc row_ror:8 row_mask:0xf bank_mask:0xf
	v_cndmask_b32_dpp v11, v203, v11, vcc row_ror:8 row_mask:0xf bank_mask:0xf
	s_waitcnt vmcnt(8)
	v_pk_fma_f32 v[176:177], v[12:13], v[116:117], v[176:177]
	v_pk_fma_f32 v[178:179], v[14:15], v[118:119], v[178:179]
	v_pk_fma_f32 v[180:181], v[8:9], v[116:117], v[180:181]
	v_pk_fma_f32 v[182:183], v[10:11], v[118:119], v[182:183]
	global_store_dwordx4 v147, v[176:179], s[38:39] offset:512
	global_store_dwordx4 v216, v[180:183], s[38:39] offset:512
	s_mov_b32 s90, -1
	s_branch .LBB0_1705
